# grid barrier after attention replaced by a producer-list sync (epoch word per workgroup, out_ln waits for the 16 workgroups covering its panel), write-through attention output
# baseline (speedup 1.0000x reference)
.LBB0_29:
	s_add_i32 s29, s41, 1
	s_movk_i32 s30, 0xe000
	v_add_co_u32_e32 v60, vcc, s30, v96
	s_bitcmp1_b32 s41, 0
	s_mov_b64 s[30:31], 0x4000
	global_load_dwordx4 v[40:43], v[96:97], off
	global_load_dwordx4 v[32:35], v[98:99], off
	global_load_dwordx4 v[36:39], v[100:101], off
	v_addc_co_u32_e32 v61, vcc, -1, v97, vcc
	v_lshl_add_u64 v[96:97], v[96:97], 0, s[30:31]
	s_cselect_b32 s30, 0xd800, 0
	v_add_u32_e32 v127, s30, v125
	global_load_dwordx4 v[60:63], v[60:61], off
	ds_read_b128 v[66:69], v127
	ds_read_b128 v[70:73], v127 offset:4608
	ds_read_b128 v[110:113], v127 offset:64
	ds_read_b128 v[128:131], v127 offset:4672
	v_mov_b32_e32 v64, v103
	s_waitcnt vmcnt(7) lgkmcnt(3)
	v_mfma_f32_16x16x32_bf16 v[66:69], v[66:69], v[12:15], 0
	ds_read_b128 v[102:105], v127 offset:9216
	ds_read_b128 v[106:109], v127 offset:13824
	v_mov_b32_e32 v126, v65
	s_waitcnt lgkmcnt(4)
	v_mfma_f32_16x16x32_bf16 v[70:73], v[70:73], v[12:15], 0
	s_bitcmp1_b32 s29, 0
	s_cselect_b32 s30, 0xd800, 0
	s_add_i32 s30, s30, 0
	s_waitcnt vmcnt(6) lgkmcnt(3)
	v_mfma_f32_16x16x32_bf16 v[66:69], v[110:113], v[8:11], v[66:69]
	ds_read_b128 v[110:113], v127 offset:9280
	v_lshl_add_u64 v[98:99], v[98:99], 0, s[86:87]
	v_lshl_add_u64 v[100:101], v[100:101], 0, s[86:87]
	s_waitcnt lgkmcnt(3)
	v_mfma_f32_16x16x32_bf16 v[70:73], v[128:131], v[8:11], v[70:73]
	ds_read_b128 v[128:131], v127 offset:13888
	s_mov_b32 s41, s29
	s_cmp_eq_u32 s28, s29
	s_waitcnt lgkmcnt(3)
	v_mfma_f32_16x16x32_bf16 v[102:105], v[102:105], v[12:15], 0
	s_waitcnt lgkmcnt(2)
	v_mfma_f32_16x16x32_bf16 v[106:109], v[106:109], v[12:15], 0
	s_waitcnt lgkmcnt(1)
	v_mfma_f32_16x16x32_bf16 v[102:105], v[110:113], v[8:11], v[102:105]
	ds_read_b128 v[110:113], v127 offset:128
	s_waitcnt lgkmcnt(1)
	v_mfma_f32_16x16x32_bf16 v[106:109], v[128:131], v[8:11], v[106:109]
	ds_read_b128 v[128:131], v127 offset:4736
	s_waitcnt vmcnt(5) lgkmcnt(1)
	v_mfma_f32_16x16x32_bf16 v[66:69], v[110:113], v[4:7], v[66:69]
	ds_read_b128 v[110:113], v127 offset:9344
	s_waitcnt lgkmcnt(1)
	v_mfma_f32_16x16x32_bf16 v[128:131], v[128:131], v[4:7], v[70:73]
	s_nop 2
	ds_read_b128 v[70:73], v127 offset:13952
	s_waitcnt lgkmcnt(1)
	v_mfma_f32_16x16x32_bf16 v[102:105], v[110:113], v[4:7], v[102:105]
	ds_read_b128 v[110:113], v127 offset:192
	ds_read_b128 v[132:135], v127 offset:4800
	ds_read_b128 v[136:139], v127 offset:9408
	ds_read_b128 v[140:143], v127 offset:14016
	ds_read_b128 v[148:151], v127 offset:18432
	s_waitcnt lgkmcnt(5)
	v_mfma_f32_16x16x32_bf16 v[106:109], v[70:73], v[4:7], v[106:109]
	s_waitcnt vmcnt(4) lgkmcnt(4)
	v_mfma_f32_16x16x32_bf16 v[66:69], v[110:113], v[0:3], v[66:69]
	ds_read_b128 v[152:155], v127 offset:18496
	ds_read_b128 v[112:115], v127 offset:23040
	ds_read_b128 v[72:75], v127 offset:23104
	s_waitcnt lgkmcnt(6)
	v_mfma_f32_16x16x32_bf16 v[128:131], v[132:135], v[0:3], v[128:131]
	s_nop 2
	v_max3_f32 v65, v66, v67, v68
	ds_read_b128 v[132:135], v127 offset:27648
	ds_read_b128 v[174:177], v127 offset:32256
	ds_read_b128 v[178:181], v127 offset:36864
	ds_read_b128 v[182:185], v127 offset:41472
	ds_read_b128 v[186:189], v127 offset:46080
	ds_read_b128 v[190:193], v127 offset:50688
	s_waitcnt lgkmcnt(11)
	v_mfma_f32_16x16x32_bf16 v[136:139], v[136:139], v[0:3], v[102:105]
	v_max_f32_e32 v70, v130, v130
	v_max_f32_e32 v71, v129, v129
	v_max3_f32 v65, v65, v69, v128
	s_waitcnt lgkmcnt(10)
	v_mfma_f32_16x16x32_bf16 v[104:107], v[140:143], v[0:3], v[106:109]
	v_max_f32_e32 v70, v71, v70
	s_nop 1
	v_max_f32_e32 v103, v138, v138
	v_max3_f32 v65, v65, v70, v131
	v_max_f32_e32 v108, v137, v137
	v_max_f32_e32 v71, v108, v103
	s_nop 0
	v_max_f32_e32 v109, v106, v106
	v_max_f32_e32 v110, v105, v105
	v_max3_f32 v65, v65, v136, v71
	v_max_f32_e32 v103, v110, v109
	v_max3_f32 v65, v65, v139, v104
	v_max3_f32 v65, v65, v103, v107
	ds_bpermute_b32 v70, v121, v65
	v_mov_b32_e32 v102, v104
	s_waitcnt lgkmcnt(0)
	v_max_f32_e32 v70, v70, v70
	v_max_f32_e32 v65, v65, v70
	ds_bpermute_b32 v70, v122, v65
	s_waitcnt lgkmcnt(0)
	v_max3_f32 v103, v64, v65, v70
	v_sub_f32_e32 v70, v64, v103
	v_pk_mul_f32 v[64:65], v[102:103], s[56:57]
	v_mul_f32_e32 v70, 0x3e0293ee, v70
	v_fmamk_f32 v66, v66, 0x3e0293ee, v65
	v_fmamk_f32 v67, v67, 0x3e0293ee, v65
	v_fmamk_f32 v68, v68, 0x3e0293ee, v65
	v_fmamk_f32 v69, v69, 0x3e0293ee, v65
	v_fmamk_f32 v71, v128, 0x3e0293ee, v65
	v_fmamk_f32 v108, v129, 0x3e0293ee, v65
	v_fmamk_f32 v109, v130, 0x3e0293ee, v65
	v_fmamk_f32 v110, v131, 0x3e0293ee, v65
	v_fmamk_f32 v111, v136, 0x3e0293ee, v65
	v_fmamk_f32 v130, v137, 0x3e0293ee, v65
	v_fmamk_f32 v131, v138, 0x3e0293ee, v65
	v_fmamk_f32 v136, v139, 0x3e0293ee, v65
	v_add_f32_e32 v64, v64, v65
	v_fmamk_f32 v137, v105, 0x3e0293ee, v65
	v_fmamk_f32 v138, v106, 0x3e0293ee, v65
	v_fmac_f32_e32 v65, 0x3e0293ee, v107
	v_exp_f32_e32 v102, v70
	v_exp_f32_e32 v104, v66
	v_exp_f32_e32 v106, v67
	v_exp_f32_e32 v105, v68
	v_exp_f32_e32 v107, v69
	v_exp_f32_e32 v66, v71
	v_exp_f32_e32 v128, v108
	v_exp_f32_e32 v67, v109
	v_exp_f32_e32 v129, v110
	v_cvt_pk_bf16_f32 v68, v104, v106
	v_cvt_pk_bf16_f32 v69, v105, v107
	v_cvt_pk_bf16_f32 v70, v66, v128
	v_cvt_pk_bf16_f32 v71, v67, v129
	v_pk_mul_f32 v[26:27], v[26:27], v[102:103] op_sel_hi:[1,0]
	v_pk_mul_f32 v[24:25], v[24:25], v[102:103] op_sel_hi:[1,0]
	v_pk_mul_f32 v[22:23], v[22:23], v[102:103] op_sel_hi:[1,0]
	v_pk_mul_f32 v[20:21], v[20:21], v[102:103] op_sel_hi:[1,0]
	v_mfma_f32_16x16x32_bf16 v[24:27], v[112:115], v[68:71], v[24:27]
	v_add_f32_e64 v114, v66, v128
	v_add_f32_e64 v115, v67, v129
	v_exp_f32_e32 v109, v111
	v_pk_add_f32 v[114:115], v[114:115], v[114:115] op_sel_hi:[0,1]
	v_exp_f32_e32 v111, v130
	v_exp_f32_e32 v147, v131
	v_exp_f32_e32 v173, v136
	v_exp_f32_e32 v108, v64
	v_pk_mul_f32 v[18:19], v[18:19], v[102:103] op_sel_hi:[1,0]
	v_pk_mul_f32 v[16:17], v[16:17], v[102:103] op_sel_hi:[1,0]
	v_exp_f32_e32 v110, v137
	v_exp_f32_e32 v112, v65
	v_mfma_f32_16x16x32_bf16 v[20:23], v[132:135], v[68:71], v[20:23]
	v_mul_f32_e64 v58, v58, v102
	v_mul_f32_e64 v59, v59, v102
	v_pk_mul_f32 v[56:57], v[56:57], v[102:103] op_sel_hi:[1,0]
	v_pk_mul_f32 v[54:55], v[54:55], v[102:103] op_sel_hi:[1,0]
	v_pk_mul_f32 v[52:53], v[52:53], v[102:103] op_sel_hi:[1,0]
	v_pk_mul_f32 v[66:67], v[50:51], v[102:103] op_sel_hi:[1,0]
	v_pk_mul_f32 v[64:65], v[48:49], v[102:103] op_sel_hi:[1,0]
	v_pk_mul_f32 v[130:131], v[46:47], v[102:103] op_sel_hi:[1,0]
	v_pk_mul_f32 v[128:129], v[44:45], v[102:103] op_sel_hi:[1,0]
	v_pk_mul_f32 v[134:135], v[30:31], v[102:103] op_sel_hi:[1,0]
	v_pk_mul_f32 v[132:133], v[28:29], v[102:103] op_sel_hi:[1,0]
	v_exp_f32_e32 v114, v138
	v_mfma_f32_16x16x32_bf16 v[16:19], v[148:151], v[68:71], v[16:19]
	v_cvt_pk_bf16_f32 v28, v109, v111
	v_cvt_pk_bf16_f32 v29, v147, v173
	v_cvt_pk_bf16_f32 v30, v108, v110
	v_mfma_f32_16x16x32_bf16 v[56:59], v[174:177], v[68:71], v[56:59]
	v_cvt_pk_bf16_f32 v31, v114, v112
	v_add3_u32 v48, s30, v123, v119
	v_add_f32_e32 v109, v109, v111
	v_mfma_f32_16x16x32_bf16 v[50:53], v[178:181], v[68:71], v[52:55]
	v_add_f32_e32 v111, v147, v173
	v_mfma_f32_16x16x32_bf16 v[44:47], v[182:185], v[68:71], v[64:67]
	v_mfma_f32_16x16x32_bf16 v[64:67], v[186:189], v[68:71], v[128:131]
	v_mfma_f32_16x16x32_bf16 v[68:71], v[190:193], v[68:71], v[132:135]
	s_nop 1
	ds_read_b128 v[128:131], v127 offset:27712
	ds_read_b128 v[132:135], v127 offset:32320
	v_mfma_f32_16x16x32_bf16 v[24:27], v[72:75], v[28:31], v[24:27]
	ds_read_b128 v[72:75], v127 offset:36928
	ds_read_b128 v[136:139], v127 offset:41536
	ds_read_b128 v[140:143], v127 offset:46144
	s_waitcnt lgkmcnt(4)
	v_mfma_f32_16x16x32_bf16 v[20:23], v[128:131], v[28:31], v[20:23]
	ds_read_b128 v[128:131], v127 offset:50752
	v_add3_u32 v127, s30, v117, v118
	s_waitcnt lgkmcnt(3)
	v_mfma_f32_16x16x32_bf16 v[52:55], v[72:75], v[28:31], v[50:53]
	v_add_f32_e64 v72, v104, v106
	v_add_f32_e64 v73, v105, v107
	v_add_u32_e32 v74, 0x9000, v48
	v_add_f32_e32 v75, v72, v73
	v_add_f32_e32 v113, 0, v75
	v_mfma_f32_16x16x32_bf16 v[16:19], v[152:155], v[28:31], v[16:19]
	v_add_f32_e64 v72, v108, v110
	v_add_f32_e64 v73, v109, v111
	v_mfma_f32_16x16x32_bf16 v[56:59], v[132:135], v[28:31], v[56:59]
	v_add_u32_e32 v132, 0x4800, v48
	s_waitcnt vmcnt(3)
	ds_write_b128 v127, v[40:43] offset:9216
	s_waitcnt vmcnt(0)
	ds_write_b128 v127, v[60:63]
	ds_write2_b64 v132, v[32:33], v[34:35] offset1:2
	ds_write2_b64 v74, v[36:37], v[38:39] offset1:2
	s_waitcnt lgkmcnt(0)
	v_mfma_f32_16x16x32_bf16 v[48:51], v[136:139], v[28:31], v[44:47]
	s_barrier
	v_mfma_f32_16x16x32_bf16 v[44:47], v[140:143], v[28:31], v[64:67]
	s_nop 2
	v_add_f32_e64 v64, v114, v112
	v_add_f32_e64 v65, v115, v113
	v_mfma_f32_16x16x32_bf16 v[28:31], v[128:131], v[28:31], v[68:71]
	v_add_f32_e64 v64, v72, v64
	v_add_f32_e64 v65, v73, v65
	v_add_f32_e32 v65, v64, v65
	v_fmac_f32_e32 v65, v126, v102
	s_cbranch_scc0 .LBB0_29
	v_add3_u32 v100, s30, v120, v124
	ds_read_b128 v[32:35], v100
	ds_read_b128 v[36:39], v100 offset:64
	ds_read_b128 v[40:43], v100 offset:4608
	ds_read_b128 v[60:63], v100 offset:4672
	ds_read_b128 v[66:69], v100 offset:128
	s_lshl_b32 s84, s40, 1
	s_waitcnt lgkmcnt(4)
	v_mfma_f32_16x16x32_bf16 v[32:35], v[32:35], v[12:15], 0
	s_waitcnt lgkmcnt(3)
	v_mfma_f32_16x16x32_bf16 v[32:35], v[36:39], v[8:11], v[32:35]
	ds_read_b128 v[36:39], v100 offset:192
	s_waitcnt lgkmcnt(1)
	v_mfma_f32_16x16x32_bf16 v[32:35], v[66:69], v[4:7], v[32:35]
	ds_read_b128 v[66:69], v100 offset:9344
	v_mfma_f32_16x16x32_bf16 v[40:43], v[40:43], v[12:15], 0
	s_waitcnt lgkmcnt(1)
	v_mfma_f32_16x16x32_bf16 v[32:35], v[36:39], v[0:3], v[32:35]
	ds_read_b128 v[36:39], v100 offset:4736
	v_mfma_f32_16x16x32_bf16 v[40:43], v[60:63], v[8:11], v[40:43]
	ds_read_b128 v[60:63], v100 offset:4800
	s_nop 4
	v_max3_f32 v64, v32, v33, v34
	s_waitcnt lgkmcnt(1)
	v_mfma_f32_16x16x32_bf16 v[36:39], v[36:39], v[4:7], v[40:43]
	s_nop 2
	ds_read_b128 v[40:43], v100 offset:9216
	s_waitcnt lgkmcnt(1)
	v_mfma_f32_16x16x32_bf16 v[36:39], v[60:63], v[0:3], v[36:39]
	ds_read_b128 v[60:63], v100 offset:9280
	s_waitcnt lgkmcnt(1)
	v_mfma_f32_16x16x32_bf16 v[40:43], v[40:43], v[12:15], 0
	s_nop 4
	v_max3_f32 v64, v64, v35, v36
	s_waitcnt lgkmcnt(0)
	v_mfma_f32_16x16x32_bf16 v[40:43], v[60:63], v[8:11], v[40:43]
	ds_read_b128 v[60:63], v100 offset:9408
	v_mfma_f32_16x16x32_bf16 v[40:43], v[66:69], v[4:7], v[40:43]
	ds_read_b128 v[66:69], v100 offset:13824
	ds_read_b128 v[70:73], v100 offset:13888
	s_waitcnt lgkmcnt(1)
	v_mfma_f32_16x16x32_bf16 v[12:15], v[66:69], v[12:15], 0
	v_max_f32_e32 v66, v38, v38
	v_max_f32_e32 v67, v37, v37
	v_mfma_f32_16x16x32_bf16 v[40:43], v[60:63], v[0:3], v[40:43]
	ds_read_b128 v[60:63], v100 offset:13952
	ds_read_b128 v[96:99], v100 offset:14016
	s_waitcnt lgkmcnt(2)
	v_mfma_f32_16x16x32_bf16 v[8:11], v[70:73], v[8:11], v[12:15]
	s_waitcnt lgkmcnt(1)
	v_mfma_f32_16x16x32_bf16 v[4:7], v[60:63], v[4:7], v[8:11]
	s_nop 0
	v_max_f32_e32 v12, v67, v66
	v_max_f32_e32 v13, v42, v42
	v_max3_f32 v12, v64, v12, v39
	s_waitcnt lgkmcnt(0)
	v_mfma_f32_16x16x32_bf16 v[0:3], v[96:99], v[0:3], v[4:7]
	v_max_f32_e32 v8, v41, v41
	v_max_f32_e32 v8, v8, v13
	v_max3_f32 v8, v12, v40, v8
	s_nop 4
	v_max_f32_e32 v5, v2, v2
	v_max_f32_e32 v6, v1, v1
	v_max3_f32 v4, v8, v43, v0
	v_max_f32_e32 v5, v6, v5
	v_max3_f32 v4, v4, v5, v3
	ds_bpermute_b32 v5, v121, v4
	s_waitcnt lgkmcnt(0)
	v_max_f32_e32 v5, v5, v5
	v_max_f32_e32 v60, v4, v5
	ds_bpermute_b32 v61, v122, v60
	ds_read_b128 v[4:7], v100 offset:18432
	ds_read_b128 v[8:11], v100 offset:18496
	ds_read_b128 v[12:15], v100 offset:23040
	s_waitcnt lgkmcnt(3)
	v_max3_f32 v61, v103, v60, v61
	v_sub_f32_e32 v60, v103, v61
	v_mul_f32_e32 v60, 0x3e0293ee, v60
	v_exp_f32_e32 v64, v60
	v_mov_b32_e32 v60, v3
	v_pk_mul_f32 v[60:61], v[60:61], s[56:57]
	v_pk_mul_f32 v[22:23], v[22:23], v[64:65] op_sel_hi:[1,0]
	v_fmamk_f32 v3, v32, 0x3e0293ee, v61
	v_exp_f32_e32 v66, v3
	v_fmamk_f32 v3, v33, 0x3e0293ee, v61
	v_fmamk_f32 v33, v37, 0x3e0293ee, v61
	v_exp_f32_e32 v68, v3
	v_fmamk_f32 v3, v34, 0x3e0293ee, v61
	v_fmamk_f32 v32, v36, 0x3e0293ee, v61
	v_exp_f32_e32 v36, v33
	v_fmamk_f32 v33, v38, 0x3e0293ee, v61
	v_fmamk_f32 v34, v39, 0x3e0293ee, v61
	v_exp_f32_e32 v32, v32
	v_exp_f32_e32 v33, v33
	v_exp_f32_e32 v37, v34
	v_exp_f32_e32 v67, v3
	v_fmamk_f32 v3, v35, 0x3e0293ee, v61
	v_exp_f32_e32 v69, v3
	v_fmamk_f32 v3, v40, 0x3e0293ee, v61
	v_fmamk_f32 v0, v0, 0x3e0293ee, v61
	v_pk_add_f32 v[34:35], v[32:33], v[36:37]
	v_exp_f32_e32 v73, v3
	v_fmamk_f32 v3, v41, 0x3e0293ee, v61
	v_exp_f32_e32 v72, v0
	v_fmamk_f32 v0, v1, 0x3e0293ee, v61
	v_pk_add_f32 v[70:71], v[34:35], v[34:35] op_sel_hi:[0,1]
	v_exp_f32_e32 v75, v3
	v_fmamk_f32 v3, v42, 0x3e0293ee, v61
	v_exp_f32_e32 v74, v0
	v_fmamk_f32 v0, v2, 0x3e0293ee, v61
	v_exp_f32_e32 v97, v3
	v_fmamk_f32 v3, v43, 0x3e0293ee, v61
	v_exp_f32_e32 v70, v0
	v_add_f32_e32 v0, v60, v61
	v_exp_f32_e32 v98, v3
	v_exp_f32_e32 v96, v0
	v_pk_mul_f32 v[2:3], v[18:19], v[64:65] op_sel_hi:[1,0]
	v_pk_mul_f32 v[0:1], v[16:17], v[64:65] op_sel_hi:[1,0]
	v_cvt_pk_bf16_f32 v16, v66, v68
	v_cvt_pk_bf16_f32 v17, v67, v69
	v_cvt_pk_bf16_f32 v18, v32, v36
	v_cvt_pk_bf16_f32 v19, v33, v37
	v_cvt_pk_bf16_f32 v32, v73, v75
	v_cvt_pk_bf16_f32 v33, v97, v98
	s_waitcnt lgkmcnt(2)
	v_mfma_f32_16x16x32_bf16 v[0:3], v[4:7], v[16:19], v[0:3]
	ds_read_b128 v[4:7], v100 offset:23104
	v_cvt_pk_bf16_f32 v34, v72, v74
	v_cvt_pk_bf16_f32 v35, v70, v96
	v_pk_mul_f32 v[20:21], v[20:21], v[64:65] op_sel_hi:[1,0]
	v_pk_mul_f32 v[54:55], v[54:55], v[64:65] op_sel_hi:[1,0]
	s_waitcnt lgkmcnt(2)
	v_mfma_f32_16x16x32_bf16 v[0:3], v[8:11], v[32:35], v[0:3]
	v_mul_f32_e64 v10, v26, v64
	v_mul_f32_e64 v11, v27, v64
	v_pk_mul_f32 v[8:9], v[24:25], v[64:65] op_sel_hi:[1,0]
	v_pk_mul_f32 v[26:27], v[58:59], v[64:65] op_sel_hi:[1,0]
	v_pk_mul_f32 v[24:25], v[56:57], v[64:65] op_sel_hi:[1,0]
	s_waitcnt lgkmcnt(1)
	v_mfma_f32_16x16x32_bf16 v[8:11], v[12:15], v[16:19], v[8:11]
	ds_read_b128 v[12:15], v100 offset:27648
	v_pk_mul_f32 v[52:53], v[52:53], v[64:65] op_sel_hi:[1,0]
	v_pk_add_f32 v[66:67], v[66:67], v[68:69]
	s_waitcnt lgkmcnt(1)
	v_mfma_f32_16x16x32_bf16 v[4:7], v[4:7], v[32:35], v[8:11]
	v_add_f32_e32 v66, v66, v67
	v_add_f32_e32 v73, v73, v75
	v_add_f32_e32 v75, v97, v98
	ds_read_b128 v[8:11], v100 offset:27712
	s_waitcnt lgkmcnt(1)
	v_mfma_f32_16x16x32_bf16 v[12:15], v[12:15], v[16:19], v[20:23]
	v_add_f32_e32 v97, 0, v66
	v_pk_mul_f32 v[30:31], v[30:31], v[64:65] op_sel_hi:[1,0]
	s_nop 0
	ds_read_b128 v[20:23], v100 offset:32256
	s_waitcnt lgkmcnt(1)
	v_mfma_f32_16x16x32_bf16 v[8:11], v[8:11], v[32:35], v[12:15]
	s_nop 2
	ds_read_b128 v[12:15], v100 offset:32320
	v_pk_mul_f32 v[28:29], v[28:29], v[64:65] op_sel_hi:[1,0]
	s_waitcnt lgkmcnt(1)
	v_mfma_f32_16x16x32_bf16 v[20:23], v[20:23], v[16:19], v[24:27]
	s_nop 2
	ds_read_b128 v[24:27], v100 offset:36864
	ds_read_b128 v[36:39], v100 offset:36928
	s_waitcnt lgkmcnt(1)
	v_mfma_f32_16x16x32_bf16 v[24:27], v[24:27], v[16:19], v[52:55]
	v_mfma_f32_16x16x32_bf16 v[12:15], v[12:15], v[32:35], v[20:23]
	s_nop 2
	ds_read_b128 v[20:23], v100 offset:41472
	ds_read_b128 v[40:43], v100 offset:41536
	ds_read_b128 v[52:55], v100 offset:46080
	ds_read_b128 v[56:59], v100 offset:46144
	ds_read_b128 v[60:63], v100 offset:50688
	s_waitcnt lgkmcnt(5)
	v_mfma_f32_16x16x32_bf16 v[24:27], v[36:39], v[32:35], v[24:27]
	v_mul_f32_e64 v38, v50, v64
	v_mul_f32_e64 v39, v51, v64
	v_pk_mul_f32 v[36:37], v[48:49], v[64:65] op_sel_hi:[1,0]
	s_waitcnt lgkmcnt(4)
	s_nop 0
	v_mfma_f32_16x16x32_bf16 v[20:23], v[20:23], v[16:19], v[36:39]
	s_waitcnt lgkmcnt(3)
	v_mfma_f32_16x16x32_bf16 v[20:23], v[40:43], v[32:35], v[20:23]
	v_add_f32_e64 v40, v72, v74
	v_add_f32_e64 v41, v73, v75
	v_pk_add_f32 v[42:43], v[70:71], v[96:97]
	v_pk_mul_f32 v[36:37], v[44:45], v[64:65] op_sel_hi:[1,0]
	v_pk_add_f32 v[40:41], v[40:41], v[42:43]
	v_pk_mul_f32 v[38:39], v[46:47], v[64:65] op_sel_hi:[1,0]
	v_add_f32_e32 v44, v40, v41
	v_fmac_f32_e32 v44, v65, v64
	ds_bpermute_b32 v45, v121, v44
	s_waitcnt lgkmcnt(3)
	v_mfma_f32_16x16x32_bf16 v[36:39], v[52:55], v[16:19], v[36:39]
	ds_read_b128 v[40:43], v100 offset:50752
	s_waitcnt lgkmcnt(0)
	s_barrier
	v_mfma_f32_16x16x32_bf16 v[16:19], v[60:63], v[16:19], v[28:31]
	s_nop 2
	v_add_f32_e32 v28, v44, v45
	ds_bpermute_b32 v29, v122, v28
	v_mfma_f32_16x16x32_bf16 v[36:39], v[56:59], v[32:35], v[36:39]
	s_waitcnt lgkmcnt(0)
	v_add_f32_e32 v28, v28, v29
	v_div_scale_f32 v29, s[28:29], v28, v28, 1.0
	v_rcp_f32_e32 v30, v29
	v_mfma_f32_16x16x32_bf16 v[16:19], v[40:43], v[32:35], v[16:19]
	v_fma_f32 v31, -v29, v30, 1.0
	v_fmac_f32_e32 v30, v31, v30
	v_div_scale_f32 v31, vcc, 1.0, v28, 1.0
	v_mul_f32_e32 v32, v31, v30
	v_fma_f32 v33, -v29, v32, v31
	v_fmac_f32_e32 v32, v33, v30
	v_fma_f32 v29, -v29, v32, v31
	v_div_fmas_f32 v29, v29, v30, v32
	v_div_fixup_f32 v28, v29, v28, 1.0
	v_lshl_add_u64 v[30:31], s[24:25], 0, v[94:95]
	v_lshl_add_u64 v[30:31], v[30:31], 0, s[84:85]
	v_pk_mul_f32 v[2:3], v[2:3], v[28:29] op_sel_hi:[1,0]
	v_pk_mul_f32 v[0:1], v[0:1], v[28:29] op_sel_hi:[1,0]
	v_lshl_add_u64 v[30:31], v[30:31], 0, v[144:145]
	v_cvt_pk_bf16_f32 v0, v0, v1
	v_cvt_pk_bf16_f32 v1, v2, v3
	global_store_dwordx2 v[30:31], v[0:1], off sc1
	v_pk_mul_f32 v[0:1], v[6:7], v[28:29] op_sel_hi:[1,0]
	v_pk_mul_f32 v[2:3], v[4:5], v[28:29] op_sel_hi:[1,0]
	s_nop 0
	v_cvt_pk_bf16_f32 v2, v2, v3
	v_cvt_pk_bf16_f32 v3, v0, v1
	global_store_dwordx2 v[30:31], v[2:3], off offset:32 sc1
	v_pk_mul_f32 v[0:1], v[10:11], v[28:29] op_sel_hi:[1,0]
	v_pk_mul_f32 v[2:3], v[8:9], v[28:29] op_sel_hi:[1,0]
	s_nop 0
	v_cvt_pk_bf16_f32 v2, v2, v3
	v_cvt_pk_bf16_f32 v3, v0, v1
	global_store_dwordx2 v[30:31], v[2:3], off offset:64 sc1
	v_pk_mul_f32 v[0:1], v[14:15], v[28:29] op_sel_hi:[1,0]
	v_pk_mul_f32 v[2:3], v[12:13], v[28:29] op_sel_hi:[1,0]
	s_nop 0
	v_cvt_pk_bf16_f32 v2, v2, v3
	v_cvt_pk_bf16_f32 v3, v0, v1
	global_store_dwordx2 v[30:31], v[2:3], off offset:96 sc1
	v_pk_mul_f32 v[0:1], v[26:27], v[28:29] op_sel_hi:[1,0]
	v_pk_mul_f32 v[2:3], v[24:25], v[28:29] op_sel_hi:[1,0]
	s_nop 0
	v_cvt_pk_bf16_f32 v2, v2, v3
	v_cvt_pk_bf16_f32 v3, v0, v1
	global_store_dwordx2 v[30:31], v[2:3], off offset:128 sc1
	v_pk_mul_f32 v[0:1], v[22:23], v[28:29] op_sel_hi:[1,0]
	v_pk_mul_f32 v[2:3], v[20:21], v[28:29] op_sel_hi:[1,0]
	s_nop 0
	v_cvt_pk_bf16_f32 v2, v2, v3
	v_cvt_pk_bf16_f32 v3, v0, v1
	global_store_dwordx2 v[30:31], v[2:3], off offset:160 sc1
	v_pk_mul_f32 v[0:1], v[38:39], v[28:29] op_sel_hi:[1,0]
	v_pk_mul_f32 v[2:3], v[36:37], v[28:29] op_sel_hi:[1,0]
	s_nop 0
	v_cvt_pk_bf16_f32 v2, v2, v3
	v_cvt_pk_bf16_f32 v3, v0, v1
	global_store_dwordx2 v[30:31], v[2:3], off offset:192 sc1
	s_load_dword s28, s[80:81], 0x0
	v_pk_mul_f32 v[0:1], v[18:19], v[28:29] op_sel_hi:[1,0]
	v_pk_mul_f32 v[2:3], v[16:17], v[28:29] op_sel_hi:[1,0]
	s_waitcnt lgkmcnt(0)
	s_add_i32 s33, s33, s28
	v_cvt_pk_bf16_f32 v2, v2, v3
	v_cvt_pk_bf16_f32 v3, v0, v1
	s_cmpk_gt_i32 s33, 0x1ff
	global_store_dwordx2 v[30:31], v[2:3], off offset:224 sc1
	s_cbranch_scc0 .LBB0_24

.LBB0_1498:
	s_cmp_eq_u32 s54, 10
	s_cbranch_scc1 .Las_entry
	s_cmp_eq_u32 s54, 22
	s_cbranch_scc0 .Las_no
.Las_entry:
	v_readlane_b32 s4, v254, 0
	s_add_u32 s28, s52, 0x3b00
	s_addc_u32 s29, s53, 0
	s_lshl_b32 s24, s4, 2
	v_mov_b32_e32 v0, s24
	v_mov_b32_e32 v1, s54
	global_store_dword v0, v1, s[28:29] sc1
	buffer_inv sc1
	s_and_b32 s5, s4, 31
	s_mov_b64 exec, 0xffff
	s_cmp_lt_u32 s5, 16
	s_cbranch_scc0 .Las_smp
	s_lshl_b32 s24, s5, 4
	v_add_u32_e32 v0, s24, v156
	s_branch .Las_go
.Las_smp:
	s_sub_i32 s24, s5, 16
	s_lshr_b32 s25, s24, 2
	s_and_b32 s24, s24, 3
	s_lshl_b32 s25, s25, 6
	s_lshl_b32 s24, s24, 1
	s_add_i32 s24, s24, s25
	v_lshrrev_b32_e32 v0, 1, v156
	v_lshlrev_b32_e32 v0, 3, v0
	v_and_b32_e32 v1, 1, v156
	v_add_u32_e32 v0, v0, v1
	v_add_u32_e32 v0, s24, v0
.Las_go:
	v_lshlrev_b32_e32 v0, 2, v0
	s_mov_b32 s33, 0
.Las_loop:
	global_load_dword v2, v0, s[28:29] sc1
	s_waitcnt vmcnt(0)
	v_cmp_gt_u32_e32 vcc, s54, v2
	s_cbranch_vccz .Lnb_done
	s_sleep 1
	s_add_i32 s33, s33, 1
	s_cmp_lt_u32 s33, 0x4000
	s_cbranch_scc1 .Las_loop
	s_branch .Lnb_done
